# mLSTM chunk gate scalars: 64-lane cumsum/cummax by DPP row shifts and row broadcasts instead of 15 ds_bpermute round trips (f32, sum association differs)
# baseline (speedup 1.0000x reference)
.LBB0_345:
	s_or_b64 s[50:51], s[4:5], s[50:51]
	s_and_b64 vcc, exec, s[50:51]
	s_cbranch_vccnz .LBB0_351
	v_add_f32_e32 v3, v178, v179
	s_xor_b32 s50, s53, 1
	s_mulk_i32 s50, 0xa40
	s_add_i32 s55, s50, 0
	s_add_i32 s55, s55, 0x23100
	s_nop 1
	v_add_f32_dpp v3, v3, v3 row_shr:1 row_mask:0xf bank_mask:0xf
	s_nop 1
	v_add_f32_dpp v3, v3, v3 row_shr:2 row_mask:0xf bank_mask:0xf
	s_nop 1
	v_add_f32_dpp v3, v3, v3 row_shr:4 row_mask:0xf bank_mask:0xf
	s_nop 1
	v_add_f32_dpp v3, v3, v3 row_shr:8 row_mask:0xf bank_mask:0xf
	s_nop 1
	v_add_f32_dpp v3, v3, v3 row_bcast:15 row_mask:0xa bank_mask:0xf
	s_nop 1
	v_add_f32_dpp v3, v3, v3 row_bcast:31 row_mask:0xc bank_mask:0xf
	v_sub_f32_e32 v2, v3, v179
	v_pk_add_f32 v[84:85], v[176:177], v[2:3] neg_lo:[0,1] neg_hi:[0,1]
	s_nop 0
	v_max_f32_e32 v0, v84, v85
	s_nop 1
	v_max_f32_dpp v0, v0, v0 row_shr:1 row_mask:0xf bank_mask:0xf
	s_nop 1
	v_max_f32_dpp v0, v0, v0 row_shr:2 row_mask:0xf bank_mask:0xf
	s_nop 1
	v_max_f32_dpp v0, v0, v0 row_shr:4 row_mask:0xf bank_mask:0xf
	s_nop 1
	v_max_f32_dpp v0, v0, v0 row_shr:8 row_mask:0xf bank_mask:0xf
	s_nop 1
	v_max_f32_dpp v0, v0, v0 row_bcast:15 row_mask:0xa bank_mask:0xf
	s_nop 1
	v_max_f32_dpp v0, v0, v0 row_bcast:31 row_mask:0xc bank_mask:0xf
	v_mov_b32_e32 v86, v219
	s_nop 1
	v_mov_b32_dpp v86, v0 wave_shr:1 row_mask:0xf bank_mask:0xf
	v_max_f32_e32 v87, v130, v0
	s_nop 0
	v_readlane_b32 s50, v87, 63
	v_readlane_b32 s51, v3, 63
	v_max3_f32 v86, v130, v86, v84
	s_nop 1
	v_mov_b32_e32 v131, s50
	v_mov_b32_e32 v0, s51
	v_lshl_add_u32 v90, v142, 2, s55
	s_waitcnt lgkmcnt(1)
	v_sub_f32_e32 v88, v84, v131
	v_sub_f32_e32 v89, v85, v131
	v_mul_f32_e32 v88, 0x3fb8aa3b, v88
	v_mul_f32_e32 v89, 0x3fb8aa3b, v89
	v_exp_f32_e32 v88, v88
	v_exp_f32_e32 v89, v89
	ds_write2st64_b64 v90, v[84:85], v[86:87] offset1:1
	ds_write2st64_b64 v90, v[2:3], v[88:89] offset0:2 offset1:3
	s_and_saveexec_b64 s[50:51], s[8:9]
	s_cbranch_execz .LBB0_348
	v_sub_f32_e32 v2, v130, v131
	v_mul_f32_e32 v2, 0x3fb8aa3b, v2
	v_exp_f32_e32 v132, v2
	v_mov_b32_e32 v2, s55
	ds_write_b96 v2, v[130:132] offset:2048
